# mlstm_out unit prologue: r1/r2/n-state loads issued with the tile loads (one round trip instead of two)
# speedup vs baseline: 1.0007x; 1.0007x over previous
.LBB0_578:
	s_lshl_b32 s43, s50, 5
	s_and_b32 s42, s50, 0xffffff00
	s_and_b32 s43, s43, 0xe0
	s_or_b32 s42, s43, s42
	s_bfe_u32 s43, s50, 0x50003
	s_or_b32 s44, s42, s43
	s_and_b64 s[42:43], s[58:59], exec
	s_cselect_b32 s42, s44, s50
	s_and_b32 s51, s42, 1
	s_ashr_i32 s62, s42, 9
	s_bfe_u32 s80, s42, 0x50001
	s_bfe_u32 s81, s42, 0x30006
	s_ashr_i32 s63, s62, 31
	s_lshl_b32 s42, s51, 2
	s_lshl_b64 s[60:61], s[62:63], 12
	s_lshl_b32 s82, s80, 7
	s_add_i32 s44, s42, s62
	s_or_b32 s60, s60, s82
	s_ashr_i32 s45, s44, 31
	s_lshl_b32 s83, s81, 5
	s_cmp_eq_u32 s51, 0
	s_cselect_b64 s[42:43], -1, 0
	s_and_b64 s[46:47], s[42:43], exec
	s_mov_b32 s46, 0x59000000
	s_cselect_b32 s46, s46, 0x5d000000
	v_mov_b32_e32 v3, s61
	v_or_b32_e32 v2, s60, v166
	s_add_u32 s46, s68, s46
	v_lshlrev_b64 v[2:3], 11, v[2:3]
	s_addc_u32 s47, s69, 0
	s_lshl_b32 vcc_lo, s81, 8
	v_or_b32_e32 v2, v2, v168
	v_or_b32_e32 v2, vcc_lo, v2
	v_lshlrev_b64 v[6:7], 1, v[2:3]
	v_lshl_add_u64 v[2:3], s[52:53], 0, v[6:7]
	s_barrier
	global_load_dwordx4 v[10:13], v[2:3], off
	v_lshl_add_u64 v[6:7], s[46:47], 0, v[6:7]
	global_load_dwordx4 v[14:17], v[6:7], off
	s_lshl_b64 s[44:45], s[44:45], 8
	s_or_b32 s44, s44, s83
	s_or_b32 s44, s44, s80
	v_mov_b32_e32 v3, s61
	v_or_b32_e32 v2, s60, v170
	v_lshlrev_b64 v[2:3], 11, v[2:3]
	v_or_b32_e32 v2, v2, v168
	v_or_b32_e32 v2, vcc_lo, v2
	v_lshlrev_b64 v[6:7], 1, v[2:3]
	v_lshl_add_u64 v[2:3], s[52:53], 0, v[6:7]
	global_load_dwordx4 v[18:21], v[2:3], off
	v_lshl_add_u64 v[6:7], s[46:47], 0, v[6:7]
	global_load_dwordx4 v[22:25], v[6:7], off
	v_mov_b32_e32 v3, s61
	v_or_b32_e32 v2, s60, v172
	v_lshlrev_b64 v[2:3], 11, v[2:3]
	v_or_b32_e32 v2, v2, v168
	v_or_b32_e32 v2, vcc_lo, v2
	v_lshlrev_b64 v[6:7], 1, v[2:3]
	v_lshl_add_u64 v[2:3], s[52:53], 0, v[6:7]
	global_load_dwordx4 v[26:29], v[2:3], off
	v_lshl_add_u64 v[6:7], s[46:47], 0, v[6:7]
	global_load_dwordx4 v[30:33], v[6:7], off
	v_mov_b32_e32 v3, s61
	v_or_b32_e32 v2, s60, v174
	v_lshlrev_b64 v[2:3], 11, v[2:3]
	v_or_b32_e32 v2, v2, v168
	v_or_b32_e32 v2, vcc_lo, v2
	v_lshlrev_b64 v[6:7], 1, v[2:3]
	v_lshl_add_u64 v[2:3], s[52:53], 0, v[6:7]
	global_load_dwordx4 v[34:37], v[2:3], off
	v_lshl_add_u64 v[6:7], s[46:47], 0, v[6:7]
	global_load_dwordx4 v[38:41], v[6:7], off
	v_mov_b32_e32 v3, s61
	v_or_b32_e32 v2, s60, v176
	v_lshlrev_b64 v[2:3], 11, v[2:3]
	v_or_b32_e32 v2, v2, v168
	v_or_b32_e32 v2, vcc_lo, v2
	v_lshlrev_b64 v[6:7], 1, v[2:3]
	v_lshl_add_u64 v[2:3], s[52:53], 0, v[6:7]
	global_load_dwordx4 v[42:45], v[2:3], off
	v_lshl_add_u64 v[6:7], s[46:47], 0, v[6:7]
	global_load_dwordx4 v[46:49], v[6:7], off
	v_mov_b32_e32 v3, s61
	v_or_b32_e32 v2, s60, v178
	v_lshlrev_b64 v[2:3], 11, v[2:3]
	v_or_b32_e32 v2, v2, v168
	v_or_b32_e32 v2, vcc_lo, v2
	v_lshlrev_b64 v[6:7], 1, v[2:3]
	v_lshl_add_u64 v[2:3], s[52:53], 0, v[6:7]
	global_load_dwordx4 v[50:53], v[2:3], off
	v_lshl_add_u64 v[6:7], s[46:47], 0, v[6:7]
	global_load_dwordx4 v[54:57], v[6:7], off
	v_mov_b32_e32 v3, s61
	v_or_b32_e32 v2, s60, v180
	v_lshlrev_b64 v[2:3], 11, v[2:3]
	v_or_b32_e32 v2, v2, v168
	v_or_b32_e32 v2, vcc_lo, v2
	v_lshlrev_b64 v[6:7], 1, v[2:3]
	v_lshl_add_u64 v[2:3], s[52:53], 0, v[6:7]
	global_load_dwordx4 v[58:61], v[2:3], off
	v_lshl_add_u64 v[6:7], s[46:47], 0, v[6:7]
	global_load_dwordx4 v[62:65], v[6:7], off
	v_mov_b32_e32 v3, s61
	v_or_b32_e32 v2, s60, v182
	v_lshlrev_b64 v[2:3], 11, v[2:3]
	v_or_b32_e32 v2, v2, v168
	v_or_b32_e32 v2, vcc_lo, v2
	v_lshlrev_b64 v[6:7], 1, v[2:3]
	v_lshl_add_u64 v[2:3], s[52:53], 0, v[6:7]
	global_load_dwordx4 v[66:69], v[2:3], off
	v_lshl_add_u64 v[6:7], s[46:47], 0, v[6:7]
	global_load_dwordx4 v[70:73], v[6:7], off
	s_and_saveexec_b64 s[46:47], s[38:39]
	s_xor_b64 s[46:47], exec, s[46:47]
	s_cbranch_execz .LBB0_582
	s_mov_b32 s83, s85
	s_mov_b64 vcc, exec
	v_readlane_b32 s84, v255, 51
	v_readlane_b32 s85, v255, 52
	s_and_b64 s[84:85], vcc, s[84:85]
	s_mov_b64 exec, s[84:85]
	s_cbranch_execz .LBB0_581
	s_lshl_b64 s[84:85], s[44:45], 10
	v_lshl_add_u64 v[2:3], v[184:185], 0, s[84:85]
	global_load_dwordx4 v[2:5], v[2:3], off
	s_waitcnt vmcnt(0)
	ds_write_b128 v209, v[2:5]

.LBB0_584:
	s_or_b64 exec, exec, s[46:47]
	v_add_u32_e32 v74, v208, v207
	s_waitcnt vmcnt(15)
	ds_write_b128 v221, v[10:13]
	s_waitcnt vmcnt(14)
	ds_write_b128 v74, v[14:17]
	s_waitcnt vmcnt(13)
	ds_write_b128 v222, v[18:21]
	s_waitcnt vmcnt(12)
	ds_write_b128 v223, v[22:25]
	s_waitcnt vmcnt(11)
	ds_write_b128 v221, v[26:29] offset:16896
	s_waitcnt vmcnt(10)
	ds_write_b128 v224, v[30:33]
	s_waitcnt vmcnt(9)
	ds_write_b128 v225, v[34:37]
	s_waitcnt vmcnt(8)
	ds_write_b128 v226, v[38:41]
	s_waitcnt vmcnt(7)
	ds_write_b128 v221, v[42:45] offset:33792
	s_waitcnt vmcnt(6)
	ds_write_b128 v227, v[46:49]
	s_waitcnt vmcnt(5)
	ds_write_b128 v228, v[50:53]
	s_waitcnt vmcnt(4)
	ds_write_b128 v229, v[54:57]
	s_waitcnt vmcnt(3)
	ds_write_b128 v221, v[58:61] offset:50688
	s_waitcnt vmcnt(2)
	ds_write_b128 v230, v[62:65]
	s_waitcnt vmcnt(1)
	ds_write_b128 v231, v[66:69]
	s_waitcnt vmcnt(0)
	ds_write_b128 v232, v[70:73]
	s_lshl_b64 s[46:47], s[44:45], 18
	v_lshl_add_u64 v[10:11], v[150:151], 0, s[46:47]
	v_add_co_u32_e32 v14, vcc, 0x80, v10
	s_waitcnt lgkmcnt(0)
	s_nop 0
	v_addc_co_u32_e32 v15, vcc, 0, v11, vcc
	s_barrier
	global_load_dwordx4 v[2:5], v[10:11], off
	global_load_dwordx4 v[6:9], v[10:11], off offset:64
	s_nop 0
	global_load_dwordx4 v[10:13], v[14:15], off
	s_nop 0
	global_load_dwordx4 v[14:17], v[14:15], off offset:64
	ds_read_b128 v[18:21], v233
	ds_read_b128 v[22:25], v233 offset:16
	ds_read_b128 v[26:29], v233 offset:32
	ds_read_b128 v[30:33], v233 offset:48
	ds_read_b128 v[34:37], v234
	ds_read_b128 v[38:41], v234 offset:16
	ds_read_b128 v[42:45], v234 offset:32
	ds_read_b128 v[46:49], v234 offset:48
	s_waitcnt lgkmcnt(7)
	v_lshlrev_b32_e32 v50, 16, v18
	v_and_b32_e32 v18, 0xffff0000, v18
	s_waitcnt lgkmcnt(3)
	v_mul_f32_e32 v18, v35, v18
	v_fmac_f32_e32 v18, v34, v50
	v_lshlrev_b32_e32 v34, 16, v19
	v_fmac_f32_e32 v18, v36, v34
	v_and_b32_e32 v19, 0xffff0000, v19
	v_fmac_f32_e32 v18, v37, v19
	v_lshlrev_b32_e32 v19, 16, v20
	s_waitcnt lgkmcnt(2)
	v_fmac_f32_e32 v18, v38, v19
	v_and_b32_e32 v19, 0xffff0000, v20
	v_fmac_f32_e32 v18, v39, v19
	v_lshlrev_b32_e32 v19, 16, v21
	v_fmac_f32_e32 v18, v40, v19
	v_and_b32_e32 v19, 0xffff0000, v21
	v_fmac_f32_e32 v18, v41, v19
	v_and_b32_e32 v19, 0xffff0000, v22
	v_add_f32_e32 v34, 0, v18
	v_lshlrev_b32_e32 v18, 16, v22
	s_waitcnt lgkmcnt(1)
	v_mul_f32_e32 v22, v43, v19
	v_fmac_f32_e32 v22, v42, v18
	v_lshlrev_b32_e32 v18, 16, v23
	v_fmac_f32_e32 v22, v44, v18
	v_and_b32_e32 v18, 0xffff0000, v23
	v_fmac_f32_e32 v22, v45, v18
	v_lshlrev_b32_e32 v18, 16, v24
	s_waitcnt lgkmcnt(0)
	v_fmac_f32_e32 v22, v46, v18
	v_and_b32_e32 v18, 0xffff0000, v24
	v_fmac_f32_e32 v22, v47, v18
	v_lshlrev_b32_e32 v18, 16, v25
	v_fmac_f32_e32 v22, v48, v18
	v_and_b32_e32 v18, 0xffff0000, v25
	v_fmac_f32_e32 v22, v49, v18
	ds_read_b128 v[18:21], v234 offset:64
	v_add_f32_e32 v34, v34, v22
	ds_read_b128 v[22:25], v234 offset:80
	v_lshlrev_b32_e32 v35, 16, v26
	v_and_b32_e32 v26, 0xffff0000, v26
	s_waitcnt lgkmcnt(1)
	v_mul_f32_e32 v26, v19, v26
	v_fmac_f32_e32 v26, v18, v35
	v_lshlrev_b32_e32 v18, 16, v27
	v_fmac_f32_e32 v26, v20, v18
	v_and_b32_e32 v18, 0xffff0000, v27
	v_fmac_f32_e32 v26, v21, v18
	v_lshlrev_b32_e32 v18, 16, v28
	s_waitcnt lgkmcnt(0)
	v_fmac_f32_e32 v26, v22, v18
	v_and_b32_e32 v18, 0xffff0000, v28
	v_fmac_f32_e32 v26, v23, v18
	v_lshlrev_b32_e32 v18, 16, v29
	v_fmac_f32_e32 v26, v24, v18
	v_and_b32_e32 v18, 0xffff0000, v29
	v_fmac_f32_e32 v26, v25, v18
	ds_read_b128 v[18:21], v234 offset:96
	ds_read_b128 v[22:25], v234 offset:112
	v_and_b32_e32 v28, 0xffff0000, v30
	v_lshlrev_b32_e32 v27, 16, v30
	v_add_f32_e32 v26, v34, v26
	s_waitcnt lgkmcnt(1)
	v_mul_f32_e32 v28, v19, v28
	v_fmac_f32_e32 v28, v18, v27
	v_lshlrev_b32_e32 v18, 16, v31
	v_fmac_f32_e32 v28, v20, v18
	v_and_b32_e32 v18, 0xffff0000, v31
	v_fmac_f32_e32 v28, v21, v18
	v_lshlrev_b32_e32 v18, 16, v32
	s_waitcnt lgkmcnt(0)
	v_fmac_f32_e32 v28, v22, v18
	v_and_b32_e32 v18, 0xffff0000, v32
	v_fmac_f32_e32 v28, v23, v18
	v_lshlrev_b32_e32 v18, 16, v33
	v_fmac_f32_e32 v28, v24, v18
	v_and_b32_e32 v18, 0xffff0000, v33
	v_fmac_f32_e32 v28, v25, v18
	ds_read_b128 v[18:21], v233 offset:64
	v_add_f32_e32 v34, v26, v28
	ds_read_b128 v[22:25], v234 offset:128
	ds_read_b128 v[26:29], v234 offset:144
	ds_read_b128 v[30:33], v233 offset:80
	s_waitcnt lgkmcnt(3)
	v_lshlrev_b32_e32 v35, 16, v18
	v_and_b32_e32 v18, 0xffff0000, v18
	s_waitcnt lgkmcnt(2)
	v_mul_f32_e32 v23, v23, v18
	v_fmac_f32_e32 v23, v22, v35
	v_lshlrev_b32_e32 v18, 16, v19
	v_fmac_f32_e32 v23, v24, v18
	v_and_b32_e32 v18, 0xffff0000, v19
	v_fmac_f32_e32 v23, v25, v18
	v_lshlrev_b32_e32 v18, 16, v20
	s_waitcnt lgkmcnt(1)
	v_fmac_f32_e32 v23, v26, v18
	v_and_b32_e32 v18, 0xffff0000, v20
	v_fmac_f32_e32 v23, v27, v18
	v_lshlrev_b32_e32 v18, 16, v21
	v_fmac_f32_e32 v23, v28, v18
	v_and_b32_e32 v18, 0xffff0000, v21
	v_fmac_f32_e32 v23, v29, v18
	ds_read_b128 v[18:21], v234 offset:160
	v_add_f32_e32 v26, v34, v23
	ds_read_b128 v[22:25], v234 offset:176
	s_waitcnt lgkmcnt(2)
	v_and_b32_e32 v28, 0xffff0000, v30
	v_lshlrev_b32_e32 v27, 16, v30
	s_waitcnt lgkmcnt(1)
	v_mul_f32_e32 v28, v19, v28
	v_fmac_f32_e32 v28, v18, v27
	v_lshlrev_b32_e32 v18, 16, v31
	v_fmac_f32_e32 v28, v20, v18
	v_and_b32_e32 v18, 0xffff0000, v31
	v_fmac_f32_e32 v28, v21, v18
	v_lshlrev_b32_e32 v18, 16, v32
	s_waitcnt lgkmcnt(0)
	v_fmac_f32_e32 v28, v22, v18
	v_and_b32_e32 v18, 0xffff0000, v32
	v_fmac_f32_e32 v28, v23, v18
	v_lshlrev_b32_e32 v18, 16, v33
	v_fmac_f32_e32 v28, v24, v18
	v_and_b32_e32 v18, 0xffff0000, v33
	v_fmac_f32_e32 v28, v25, v18
	ds_read_b128 v[18:21], v233 offset:96
	v_add_f32_e32 v34, v26, v28
	ds_read_b128 v[22:25], v234 offset:192
	ds_read_b128 v[26:29], v234 offset:208
	ds_read_b128 v[30:33], v233 offset:112
	s_waitcnt lgkmcnt(3)
	v_lshlrev_b32_e32 v35, 16, v18
	v_and_b32_e32 v18, 0xffff0000, v18
	s_waitcnt lgkmcnt(2)
	v_mul_f32_e32 v23, v23, v18
	v_fmac_f32_e32 v23, v22, v35
	v_lshlrev_b32_e32 v18, 16, v19
	v_fmac_f32_e32 v23, v24, v18
	v_and_b32_e32 v18, 0xffff0000, v19
	v_fmac_f32_e32 v23, v25, v18
	v_lshlrev_b32_e32 v18, 16, v20
	s_waitcnt lgkmcnt(1)
	v_fmac_f32_e32 v23, v26, v18
	v_and_b32_e32 v18, 0xffff0000, v20
	v_fmac_f32_e32 v23, v27, v18
	v_lshlrev_b32_e32 v18, 16, v21
	v_fmac_f32_e32 v23, v28, v18
	v_and_b32_e32 v18, 0xffff0000, v21
	v_fmac_f32_e32 v23, v29, v18
	ds_read_b128 v[18:21], v234 offset:224
	v_add_f32_e32 v26, v34, v23
	ds_read_b128 v[22:25], v234 offset:240
	s_waitcnt lgkmcnt(2)
	v_and_b32_e32 v28, 0xffff0000, v30
	v_lshlrev_b32_e32 v27, 16, v30
	s_waitcnt lgkmcnt(1)
	v_mul_f32_e32 v19, v19, v28
	v_fmac_f32_e32 v19, v18, v27
	v_lshlrev_b32_e32 v18, 16, v31
	v_fmac_f32_e32 v19, v20, v18
	v_and_b32_e32 v18, 0xffff0000, v31
	v_fmac_f32_e32 v19, v21, v18
	v_lshlrev_b32_e32 v18, 16, v32
	s_waitcnt lgkmcnt(0)
	v_fmac_f32_e32 v19, v22, v18
	v_and_b32_e32 v18, 0xffff0000, v32
	v_fmac_f32_e32 v19, v23, v18
	v_lshlrev_b32_e32 v18, 16, v33
	v_fmac_f32_e32 v19, v24, v18
	v_and_b32_e32 v18, 0xffff0000, v33
	v_fmac_f32_e32 v19, v25, v18
	v_add_f32_e32 v18, v26, v19
	ds_bpermute_b32 v19, v213, v18
	s_waitcnt lgkmcnt(0)
	v_add_f32_e32 v18, v18, v19
	ds_bpermute_b32 v19, v214, v18
	s_and_saveexec_b64 s[44:45], s[40:41]
	s_cbranch_execz .LBB0_586
	s_waitcnt lgkmcnt(0)
	v_add_f32_e32 v18, v18, v19
	ds_write_b32 v212, v18
